# h3ABpk
# speedup vs baseline: 1.0066x; 1.0009x over previous
; #define SBAR() __builtin_amdgcn_sched_barrier(0)
; #define RD8(KS, P) const s16x4 P##l0 = tr_read<v_rd_off(0, KS, 0)>(vb), P##h0 = tr_read<v_rd_off(0, KS, 1)>(vb), P##l1 = tr_read<v_rd_off(1, KS, 0)>(vb), P##h1 = tr_read<v_rd_off(1, KS, 1)>(vb), \
;                                P##l2 = tr_read<v_rd_off(2, KS, 0)>(vb), P##h2 = tr_read<v_rd_off(2, KS, 1)>(vb), P##l3 = tr_read<v_rd_off(3, KS, 0)>(vb), P##h3 = tr_read<v_rd_off(3, KS, 1)>(vb)
; DEVI void pv_all(f32x16 (&o)[4], int vb, bf16x8 pa0, bf16x8 pa1, bf16x8 pa2, bf16x8 pa3) {
;     ...
;   RD8(0, a); RD8(1, b);
;   asm volatile("s_waitcnt lgkmcnt(8)" ::: "memory"); SBAR(); MM4(a, pa0); SBAR();
;   RD8(2, c);
;   asm volatile("s_waitcnt lgkmcnt(8)" ::: "memory"); SBAR(); MM4(b, pa1); SBAR();
;   RD8(3, d);
;   asm volatile("s_waitcnt lgkmcnt(8)" ::: "memory"); SBAR(); MM4(c, pa2); SBAR();
;   asm volatile("s_waitcnt lgkmcnt(0)" ::: "memory"); SBAR(); MM4(d, pa3);
; template <bool ALIBI, bool LAST>
; DEVI void softmax_tile(f32x16& p0, f32x16& p1, const float C, const float nslope2, const float dbase, float& m_reg, float& l_reg, float& alpha,
;                        bf16x8& pa0, bf16x8& pa1, bf16x8& pa2, bf16x8& pa3) {
;     ...
;   {
;     const float mnC = -m_reg * C;
; #pragma unroll
;     for (int r = 0; r < 16; ++r) { p0[r] = __builtin_amdgcn_exp2f(fmaf(p0[r], C, mnC)); p1[r] = __builtin_amdgcn_exp2f(fmaf(p1[r], C, mnC)); }
;   }
;   float ps = 0.f;
; #pragma unroll
;   for (int r = 0; r < 16; ++r) ps += p0[r];
; #pragma unroll
;   for (int r = 0; r < 16; ++r) ps += p1[r];
;   { auto rr = __builtin_amdgcn_permlane32_swap(__float_as_uint(ps), __float_as_uint(ps), false, false);
;     ps = __uint_as_float(rr[0]) + __uint_as_float(rr[1]); }
;   l_reg = l_reg * alpha + ps;
;     ...
;   PK4(p0, 0, pa0); PK4(p0, 8, pa1); PK4(p1, 0, pa2); PK4(p1, 8, pa3);
.Lmy_B_cont:
	v_mul_f32_e32 v238, 0xbdd53b94, v199
	v_mov_b32_e32 v239, 0x3dd53b94
	ds_read_b64_tr_b16 v[220:221], v236 offset:0x1000
	ds_read_b64_tr_b16 v[222:223], v236 offset:0x1800
	ds_read_b64_tr_b16 v[224:225], v236 offset:0x1200
	ds_read_b64_tr_b16 v[226:227], v236 offset:0x1a00
	ds_read_b64_tr_b16 v[228:229], v236 offset:0x1400
	ds_read_b64_tr_b16 v[230:231], v236 offset:0x1c00
	ds_read_b64_tr_b16 v[232:233], v236 offset:0x1600
	ds_read_b64_tr_b16 v[234:235], v236 offset:0x1e00
	v_fmamk_f32 v82, v82, 0x3dd53b94, v238
	v_fmamk_f32 v83, v83, 0x3dd53b94, v238
	v_exp_f32_e32 v82, v82
	v_fmamk_f32 v84, v84, 0x3dd53b94, v238
	v_exp_f32_e32 v83, v83
	v_fmamk_f32 v85, v85, 0x3dd53b94, v238
	v_exp_f32_e32 v84, v84
	v_fmamk_f32 v86, v86, 0x3dd53b94, v238
	v_exp_f32_e32 v85, v85
	v_add_f32_e32 v237, v82, v83
	v_fmamk_f32 v87, v87, 0x3dd53b94, v238
	v_exp_f32_e32 v86, v86
	v_add_f32_e32 v237, v84, v237
	v_fmamk_f32 v88, v88, 0x3dd53b94, v238
	v_exp_f32_e32 v87, v87
	v_add_f32_e32 v237, v85, v237
	v_fmamk_f32 v89, v89, 0x3dd53b94, v238
	v_exp_f32_e32 v88, v88
	v_add_f32_e32 v237, v86, v237
	v_fmamk_f32 v90, v90, 0x3dd53b94, v238
	v_exp_f32_e32 v89, v89
	v_add_f32_e32 v237, v87, v237
	v_fmamk_f32 v91, v91, 0x3dd53b94, v238
	v_exp_f32_e32 v90, v90
	v_add_f32_e32 v237, v88, v237
	v_fmamk_f32 v92, v92, 0x3dd53b94, v238
	v_exp_f32_e32 v91, v91
	v_add_f32_e32 v237, v89, v237
	v_fmamk_f32 v93, v93, 0x3dd53b94, v238
	v_exp_f32_e32 v92, v92
	v_add_f32_e32 v237, v90, v237
	v_cvt_pk_bf16_f32 v89, v88, v89
	v_fmamk_f32 v94, v94, 0x3dd53b94, v238
	v_exp_f32_e32 v93, v93
	v_add_f32_e32 v237, v91, v237
	v_cvt_pk_bf16_f32 v88, v86, v87
	v_fmamk_f32 v95, v95, 0x3dd53b94, v238
	v_exp_f32_e32 v94, v94
	v_add_f32_e32 v237, v92, v237
	v_cvt_pk_bf16_f32 v87, v84, v85
	v_fmamk_f32 v96, v96, 0x3dd53b94, v238
	v_exp_f32_e32 v95, v95
	v_add_f32_e32 v237, v93, v237
	v_cvt_pk_bf16_f32 v86, v82, v83
	v_fmamk_f32 v97, v97, 0x3dd53b94, v238
	v_exp_f32_e32 v96, v96
	v_add_f32_e32 v237, v94, v237
	v_fmamk_f32 v66, v66, 0x3dd53b94, v238
	v_exp_f32_e32 v97, v97
	v_add_f32_e32 v237, v95, v237
	v_permlane32_swap_b32_e32 v86, v88
	v_fmamk_f32 v67, v67, 0x3dd53b94, v238
	v_exp_f32_e32 v66, v66
	v_add_f32_e32 v237, v96, v237
	v_permlane32_swap_b32_e32 v87, v89
	v_fmamk_f32 v68, v68, 0x3dd53b94, v238
	v_exp_f32_e32 v67, v67
	v_add_f32_e32 v237, v97, v237
	v_fmamk_f32 v69, v69, 0x3dd53b94, v238
	v_exp_f32_e32 v68, v68
	v_add_f32_e32 v237, v66, v237
	v_cvt_pk_bf16_f32 v97, v96, v97
	v_fmamk_f32 v70, v70, 0x3dd53b94, v238
	v_exp_f32_e32 v69, v69
	v_add_f32_e32 v237, v67, v237
	v_cvt_pk_bf16_f32 v96, v94, v95
	v_fmamk_f32 v71, v71, 0x3dd53b94, v238
	v_exp_f32_e32 v70, v70
	v_add_f32_e32 v237, v68, v237
	v_cvt_pk_bf16_f32 v95, v92, v93
	v_fmamk_f32 v72, v72, 0x3dd53b94, v238
	v_exp_f32_e32 v71, v71
	v_add_f32_e32 v237, v69, v237
	v_cvt_pk_bf16_f32 v94, v90, v91
	v_fmamk_f32 v73, v73, 0x3dd53b94, v238
	v_exp_f32_e32 v72, v72
	v_add_f32_e32 v237, v70, v237
	v_fmamk_f32 v74, v74, 0x3dd53b94, v238
	v_exp_f32_e32 v73, v73
	v_add_f32_e32 v237, v71, v237
	v_permlane32_swap_b32_e32 v94, v96
	v_fmamk_f32 v75, v75, 0x3dd53b94, v238
	v_exp_f32_e32 v74, v74
	v_add_f32_e32 v237, v72, v237
	v_permlane32_swap_b32_e32 v95, v97
	v_fmamk_f32 v76, v76, 0x3dd53b94, v238
	v_exp_f32_e32 v75, v75
	v_add_f32_e32 v237, v73, v237
	v_fmamk_f32 v77, v77, 0x3dd53b94, v238
	v_exp_f32_e32 v76, v76
	v_add_f32_e32 v237, v74, v237
	v_cvt_pk_bf16_f32 v73, v72, v73
	v_fmamk_f32 v78, v78, 0x3dd53b94, v238
	v_exp_f32_e32 v77, v77
	v_add_f32_e32 v237, v75, v237
	v_cvt_pk_bf16_f32 v72, v70, v71
	v_fmamk_f32 v79, v79, 0x3dd53b94, v238
	v_exp_f32_e32 v78, v78
	v_add_f32_e32 v237, v76, v237
	v_cvt_pk_bf16_f32 v71, v68, v69
	v_fmamk_f32 v80, v80, 0x3dd53b94, v238
	v_exp_f32_e32 v79, v79
	v_add_f32_e32 v237, v77, v237
	v_cvt_pk_bf16_f32 v70, v66, v67
	v_fmamk_f32 v81, v81, 0x3dd53b94, v238
	v_exp_f32_e32 v80, v80
	v_add_f32_e32 v237, v78, v237
	v_exp_f32_e32 v81, v81
	v_add_f32_e32 v237, v79, v237
	v_permlane32_swap_b32_e32 v70, v72
	v_add_f32_e32 v237, v80, v237
	v_permlane32_swap_b32_e32 v71, v73
	v_add_f32_e32 v237, v81, v237
	v_cvt_pk_bf16_f32 v81, v80, v81
	v_cvt_pk_bf16_f32 v80, v78, v79
	v_cvt_pk_bf16_f32 v79, v76, v77
	v_cvt_pk_bf16_f32 v78, v74, v75
	v_mov_b32_e32 v169, v237
	s_nop 1
	v_permlane32_swap_b32_e32 v237, v169
	v_permlane32_swap_b32_e32 v78, v80
	v_permlane32_swap_b32_e32 v79, v81
	v_add_f32_e32 v169, v237, v169
	v_fmac_f32_e32 v169, v149, v168
	v_mov_b32_e32 v149, v169
	s_waitcnt lgkmcnt(8)
	v_mfma_f32_32x32x16_bf16 v[2:17], v[204:207], v[86:89], v[2:17]
	v_mfma_f32_32x32x16_bf16 v[18:33], v[208:211], v[86:89], v[18:33]
	v_mfma_f32_32x32x16_bf16 v[34:49], v[212:215], v[86:89], v[34:49]
	v_mfma_f32_32x32x16_bf16 v[50:65], v[216:219], v[86:89], v[50:65]
	ds_read_b64_tr_b16 v[204:205], v236 offset:0x2000
	ds_read_b64_tr_b16 v[206:207], v236 offset:0x2800
	ds_read_b64_tr_b16 v[208:209], v236 offset:0x2200
	ds_read_b64_tr_b16 v[210:211], v236 offset:0x2a00
	ds_read_b64_tr_b16 v[212:213], v236 offset:0x2400
	ds_read_b64_tr_b16 v[214:215], v236 offset:0x2c00
	ds_read_b64_tr_b16 v[216:217], v236 offset:0x2600
	ds_read_b64_tr_b16 v[218:219], v236 offset:0x2e00
	s_waitcnt lgkmcnt(8)
	v_mfma_f32_32x32x16_bf16 v[2:17], v[220:223], v[94:97], v[2:17]
	v_mfma_f32_32x32x16_bf16 v[18:33], v[224:227], v[94:97], v[18:33]
	v_mfma_f32_32x32x16_bf16 v[34:49], v[228:231], v[94:97], v[34:49]
	v_mfma_f32_32x32x16_bf16 v[50:65], v[232:235], v[94:97], v[50:65]
	ds_read_b64_tr_b16 v[220:221], v236 offset:0x3000
	ds_read_b64_tr_b16 v[222:223], v236 offset:0x3800
	ds_read_b64_tr_b16 v[224:225], v236 offset:0x3200
	ds_read_b64_tr_b16 v[226:227], v236 offset:0x3a00
	ds_read_b64_tr_b16 v[228:229], v236 offset:0x3400
	ds_read_b64_tr_b16 v[230:231], v236 offset:0x3c00
	ds_read_b64_tr_b16 v[232:233], v236 offset:0x3600
	ds_read_b64_tr_b16 v[234:235], v236 offset:0x3e00
	s_waitcnt lgkmcnt(8)
	v_mfma_f32_32x32x16_bf16 v[2:17], v[204:207], v[70:73], v[2:17]
	v_mfma_f32_32x32x16_bf16 v[18:33], v[208:211], v[70:73], v[18:33]
	v_mfma_f32_32x32x16_bf16 v[34:49], v[212:215], v[70:73], v[34:49]
	v_mfma_f32_32x32x16_bf16 v[50:65], v[216:219], v[70:73], v[50:65]
	s_waitcnt lgkmcnt(0)
	v_mfma_f32_32x32x16_bf16 v[2:17], v[220:223], v[78:81], v[2:17]
	v_mfma_f32_32x32x16_bf16 v[18:33], v[224:227], v[78:81], v[18:33]
	v_mfma_f32_32x32x16_bf16 v[34:49], v[228:231], v[78:81], v[34:49]
	v_mfma_f32_32x32x16_bf16 v[50:65], v[232:235], v[78:81], v[50:65]
	s_branch .LBB0_210

; #define SBAR() __builtin_amdgcn_sched_barrier(0)
; #define RD8(KS, P) const s16x4 P##l0 = tr_read<v_rd_off(0, KS, 0)>(vb), P##h0 = tr_read<v_rd_off(0, KS, 1)>(vb), P##l1 = tr_read<v_rd_off(1, KS, 0)>(vb), P##h1 = tr_read<v_rd_off(1, KS, 1)>(vb), \
;                                P##l2 = tr_read<v_rd_off(2, KS, 0)>(vb), P##h2 = tr_read<v_rd_off(2, KS, 1)>(vb), P##l3 = tr_read<v_rd_off(3, KS, 0)>(vb), P##h3 = tr_read<v_rd_off(3, KS, 1)>(vb)
; DEVI void pv_all(f32x16 (&o)[4], int vb, bf16x8 pa0, bf16x8 pa1, bf16x8 pa2, bf16x8 pa3) {
;     ...
;   RD8(0, a); RD8(1, b);
;   asm volatile("s_waitcnt lgkmcnt(8)" ::: "memory"); SBAR(); MM4(a, pa0); SBAR();
;   RD8(2, c);
;   asm volatile("s_waitcnt lgkmcnt(8)" ::: "memory"); SBAR(); MM4(b, pa1); SBAR();
;   RD8(3, d);
;   asm volatile("s_waitcnt lgkmcnt(8)" ::: "memory"); SBAR(); MM4(c, pa2); SBAR();
;   asm volatile("s_waitcnt lgkmcnt(0)" ::: "memory"); SBAR(); MM4(d, pa3);
; template <bool ALIBI, bool LAST>
; DEVI void softmax_tile(f32x16& p0, f32x16& p1, const float C, const float nslope2, const float dbase, float& m_reg, float& l_reg, float& alpha,
;                        bf16x8& pa0, bf16x8& pa1, bf16x8& pa2, bf16x8& pa3) {
;     ...
;   {
;     const float mnC = -m_reg * C;
; #pragma unroll
;     for (int r = 0; r < 16; ++r) { p0[r] = __builtin_amdgcn_exp2f(fmaf(p0[r], C, mnC)); p1[r] = __builtin_amdgcn_exp2f(fmaf(p1[r], C, mnC)); }
;   }
;   float ps = 0.f;
; #pragma unroll
;   for (int r = 0; r < 16; ++r) ps += p0[r];
; #pragma unroll
;   for (int r = 0; r < 16; ++r) ps += p1[r];
;   { auto rr = __builtin_amdgcn_permlane32_swap(__float_as_uint(ps), __float_as_uint(ps), false, false);
;     ps = __uint_as_float(rr[0]) + __uint_as_float(rr[1]); }
;   l_reg = l_reg * alpha + ps;
;     ...
;   PK4(p0, 0, pa0); PK4(p0, 8, pa1); PK4(p1, 0, pa2); PK4(p1, 8, pa3);
.Lmy_A_cont:
	v_mul_f32_e32 v208, 0xbe0293ee, v151
	v_mov_b32_e32 v209, 0x3e0293ee
	ds_read_b64_tr_b16 v[160:161], v211 offset:0x1000
	ds_read_b64_tr_b16 v[162:163], v211 offset:0x1800
	ds_read_b64_tr_b16 v[164:165], v211 offset:0x1200
	ds_read_b64_tr_b16 v[166:167], v211 offset:0x1a00
	ds_read_b64_tr_b16 v[184:185], v211 offset:0x1400
	ds_read_b64_tr_b16 v[186:187], v211 offset:0x1c00
	ds_read_b64_tr_b16 v[188:189], v211 offset:0x1600
	ds_read_b64_tr_b16 v[190:191], v211 offset:0x1e00
	v_fmamk_f32 v82, v82, 0x3e0293ee, v208
	v_fmamk_f32 v83, v83, 0x3e0293ee, v208
	v_exp_f32_e32 v82, v82
	v_fmamk_f32 v84, v84, 0x3e0293ee, v208
	v_exp_f32_e32 v83, v83
	v_fmamk_f32 v85, v85, 0x3e0293ee, v208
	v_exp_f32_e32 v84, v84
	v_fmamk_f32 v86, v86, 0x3e0293ee, v208
	v_exp_f32_e32 v85, v85
	v_add_f32_e32 v210, v82, v83
	v_fmamk_f32 v87, v87, 0x3e0293ee, v208
	v_exp_f32_e32 v86, v86
	v_add_f32_e32 v210, v84, v210
	v_fmamk_f32 v88, v88, 0x3e0293ee, v208
	v_exp_f32_e32 v87, v87
	v_add_f32_e32 v210, v85, v210
	v_fmamk_f32 v89, v89, 0x3e0293ee, v208
	v_exp_f32_e32 v88, v88
	v_add_f32_e32 v210, v86, v210
	v_fmamk_f32 v90, v90, 0x3e0293ee, v208
	v_exp_f32_e32 v89, v89
	v_add_f32_e32 v210, v87, v210
	v_fmamk_f32 v91, v91, 0x3e0293ee, v208
	v_exp_f32_e32 v90, v90
	v_add_f32_e32 v210, v88, v210
	v_fmamk_f32 v92, v92, 0x3e0293ee, v208
	v_exp_f32_e32 v91, v91
	v_add_f32_e32 v210, v89, v210
	v_fmamk_f32 v93, v93, 0x3e0293ee, v208
	v_exp_f32_e32 v92, v92
	v_add_f32_e32 v210, v90, v210
	v_cvt_pk_bf16_f32 v89, v88, v89
	v_fmamk_f32 v94, v94, 0x3e0293ee, v208
	v_exp_f32_e32 v93, v93
	v_add_f32_e32 v210, v91, v210
	v_cvt_pk_bf16_f32 v88, v86, v87
	v_fmamk_f32 v95, v95, 0x3e0293ee, v208
	v_exp_f32_e32 v94, v94
	v_add_f32_e32 v210, v92, v210
	v_cvt_pk_bf16_f32 v87, v84, v85
	v_fmamk_f32 v96, v96, 0x3e0293ee, v208
	v_exp_f32_e32 v95, v95
	v_add_f32_e32 v210, v93, v210
	v_cvt_pk_bf16_f32 v86, v82, v83
	v_fmamk_f32 v97, v97, 0x3e0293ee, v208
	v_exp_f32_e32 v96, v96
	v_add_f32_e32 v210, v94, v210
	v_fmamk_f32 v66, v66, 0x3e0293ee, v208
	v_exp_f32_e32 v97, v97
	v_add_f32_e32 v210, v95, v210
	v_permlane32_swap_b32_e32 v86, v88
	v_fmamk_f32 v67, v67, 0x3e0293ee, v208
	v_exp_f32_e32 v66, v66
	v_add_f32_e32 v210, v96, v210
	v_permlane32_swap_b32_e32 v87, v89
	v_fmamk_f32 v68, v68, 0x3e0293ee, v208
	v_exp_f32_e32 v67, v67
	v_add_f32_e32 v210, v97, v210
	v_fmamk_f32 v69, v69, 0x3e0293ee, v208
	v_exp_f32_e32 v68, v68
	v_add_f32_e32 v210, v66, v210
	v_cvt_pk_bf16_f32 v97, v96, v97
	v_fmamk_f32 v70, v70, 0x3e0293ee, v208
	v_exp_f32_e32 v69, v69
	v_add_f32_e32 v210, v67, v210
	v_cvt_pk_bf16_f32 v96, v94, v95
	v_fmamk_f32 v71, v71, 0x3e0293ee, v208
	v_exp_f32_e32 v70, v70
	v_add_f32_e32 v210, v68, v210
	v_cvt_pk_bf16_f32 v95, v92, v93
	v_fmamk_f32 v72, v72, 0x3e0293ee, v208
	v_exp_f32_e32 v71, v71
	v_add_f32_e32 v210, v69, v210
	v_cvt_pk_bf16_f32 v94, v90, v91
	v_fmamk_f32 v73, v73, 0x3e0293ee, v208
	v_exp_f32_e32 v72, v72
	v_add_f32_e32 v210, v70, v210
	v_fmamk_f32 v74, v74, 0x3e0293ee, v208
	v_exp_f32_e32 v73, v73
	v_add_f32_e32 v210, v71, v210
	v_permlane32_swap_b32_e32 v94, v96
	v_fmamk_f32 v75, v75, 0x3e0293ee, v208
	v_exp_f32_e32 v74, v74
	v_add_f32_e32 v210, v72, v210
	v_permlane32_swap_b32_e32 v95, v97
	v_fmamk_f32 v76, v76, 0x3e0293ee, v208
	v_exp_f32_e32 v75, v75
	v_add_f32_e32 v210, v73, v210
	v_fmamk_f32 v77, v77, 0x3e0293ee, v208
	v_exp_f32_e32 v76, v76
	v_add_f32_e32 v210, v74, v210
	v_cvt_pk_bf16_f32 v73, v72, v73
	v_fmamk_f32 v78, v78, 0x3e0293ee, v208
	v_exp_f32_e32 v77, v77
	v_add_f32_e32 v210, v75, v210
	v_cvt_pk_bf16_f32 v72, v70, v71
	v_fmamk_f32 v79, v79, 0x3e0293ee, v208
	v_exp_f32_e32 v78, v78
	v_add_f32_e32 v210, v76, v210
	v_cvt_pk_bf16_f32 v71, v68, v69
	v_fmamk_f32 v80, v80, 0x3e0293ee, v208
	v_exp_f32_e32 v79, v79
	v_add_f32_e32 v210, v77, v210
	v_cvt_pk_bf16_f32 v70, v66, v67
	v_fmamk_f32 v81, v81, 0x3e0293ee, v208
	v_exp_f32_e32 v80, v80
	v_add_f32_e32 v210, v78, v210
	v_exp_f32_e32 v81, v81
	v_add_f32_e32 v210, v79, v210
	v_permlane32_swap_b32_e32 v70, v72
	v_add_f32_e32 v210, v80, v210
	v_permlane32_swap_b32_e32 v71, v73
	v_add_f32_e32 v210, v81, v210
	v_cvt_pk_bf16_f32 v81, v80, v81
	v_cvt_pk_bf16_f32 v80, v78, v79
	v_cvt_pk_bf16_f32 v79, v76, v77
	v_cvt_pk_bf16_f32 v78, v74, v75
	v_mov_b32_e32 v168, v210
	s_nop 1
	v_permlane32_swap_b32_e32 v210, v168
	v_permlane32_swap_b32_e32 v78, v80
	v_permlane32_swap_b32_e32 v79, v81
	v_add_f32_e32 v168, v210, v168
	v_fmac_f32_e32 v168, v149, v144
	v_mov_b32_e32 v149, v168
	s_waitcnt lgkmcnt(8)
	v_mfma_f32_32x32x16_bf16 v[2:17], v[192:195], v[86:89], v[2:17]
	v_mfma_f32_32x32x16_bf16 v[18:33], v[196:199], v[86:89], v[18:33]
	v_mfma_f32_32x32x16_bf16 v[34:49], v[200:203], v[86:89], v[34:49]
	v_mfma_f32_32x32x16_bf16 v[50:65], v[204:207], v[86:89], v[50:65]
	ds_read_b64_tr_b16 v[192:193], v211 offset:0x2000
	ds_read_b64_tr_b16 v[194:195], v211 offset:0x2800
	ds_read_b64_tr_b16 v[196:197], v211 offset:0x2200
	ds_read_b64_tr_b16 v[198:199], v211 offset:0x2a00
	ds_read_b64_tr_b16 v[200:201], v211 offset:0x2400
	ds_read_b64_tr_b16 v[202:203], v211 offset:0x2c00
	ds_read_b64_tr_b16 v[204:205], v211 offset:0x2600
	ds_read_b64_tr_b16 v[206:207], v211 offset:0x2e00
	s_waitcnt lgkmcnt(8)
	v_mfma_f32_32x32x16_bf16 v[2:17], v[160:163], v[94:97], v[2:17]
	v_mfma_f32_32x32x16_bf16 v[18:33], v[164:167], v[94:97], v[18:33]
	v_mfma_f32_32x32x16_bf16 v[34:49], v[184:187], v[94:97], v[34:49]
	v_mfma_f32_32x32x16_bf16 v[50:65], v[188:191], v[94:97], v[50:65]
	ds_read_b64_tr_b16 v[160:161], v211 offset:0x3000
	ds_read_b64_tr_b16 v[162:163], v211 offset:0x3800
	ds_read_b64_tr_b16 v[164:165], v211 offset:0x3200
	ds_read_b64_tr_b16 v[166:167], v211 offset:0x3a00
	ds_read_b64_tr_b16 v[184:185], v211 offset:0x3400
	ds_read_b64_tr_b16 v[186:187], v211 offset:0x3c00
	ds_read_b64_tr_b16 v[188:189], v211 offset:0x3600
	ds_read_b64_tr_b16 v[190:191], v211 offset:0x3e00
	s_waitcnt lgkmcnt(8)
	v_mfma_f32_32x32x16_bf16 v[2:17], v[192:195], v[70:73], v[2:17]
	v_mfma_f32_32x32x16_bf16 v[18:33], v[196:199], v[70:73], v[18:33]
	v_mfma_f32_32x32x16_bf16 v[34:49], v[200:203], v[70:73], v[34:49]
	v_mfma_f32_32x32x16_bf16 v[50:65], v[204:207], v[70:73], v[50:65]
	s_waitcnt lgkmcnt(0)
	v_mfma_f32_32x32x16_bf16 v[2:17], v[160:163], v[78:81], v[2:17]
	v_mfma_f32_32x32x16_bf16 v[18:33], v[164:167], v[78:81], v[18:33]
	v_mfma_f32_32x32x16_bf16 v[34:49], v[184:187], v[78:81], v[34:49]
	v_mfma_f32_32x32x16_bf16 v[50:65], v[188:191], v[78:81], v[50:65]
	s_branch .LBB0_227

; #define WAIT_L(n) asm volatile("s_waitcnt lgkmcnt(%0)" ::"n"(n) : "memory")
; #define STAGE(P, BASE, OFF, kt) do { \
;     __builtin_amdgcn_global_load_lds((const unsigned*)((BASE) + (OFF[0] + (unsigned)(kt) * BK)), (unsigned*)((char*)(P) + wid * 1024), 16, 0, 0); \
;     __builtin_amdgcn_global_load_lds((const unsigned*)((BASE) + (OFF[1] + (unsigned)(kt) * BK)), (unsigned*)((char*)(P) + wid * 1024 + 8192), 16, 0, 0); } while (0)
; #define LDA(dst, b, h) for (int m = 0; m < 4; ++m) for (int k = 0; k < 2; ++k) \
;     dst[m][k] = *reinterpret_cast<const bf16x8*>((char*)SA(b, h) + lds_byte(wr * 64 + m * 16 + fr, k * 32 + fq * 8))
; #define LDB(dst, b, h) for (int n = 0; n < 2; ++n) for (int k = 0; k < 2; ++k) \
;     dst[n][k] = *reinterpret_cast<const bf16x8*>((char*)SB(b, h) + lds_byte(wc * 32 + n * 16 + fr, k * 32 + fq * 8))
; #define MMA(ai, bj, At_, Bt_) do { __builtin_amdgcn_s_setprio(1); \
;     for (int m = 0; m < 4; ++m) for (int n = 0; n < 2; ++n) for (int k = 0; k < 2; ++k) \
;       acc[ai][bj][m][n] = __builtin_amdgcn_mfma_f32_16x16x32_bf16(Bt_[n][k], At_[m][k], acc[ai][bj][m][n], 0, 0, 0); \
;     __builtin_amdgcn_s_setprio(0); } while (0)
; #define BAR __builtin_amdgcn_s_barrier()
; #define SCHED __builtin_amdgcn_sched_barrier(0)
; DEVI void gemm_tile(const Params& p, int layer, const u16* __restrict__ A, unsigned lda, const u16* __restrict__ Bt, unsigned ldb, int K,
;                     int brow, int bcol, int ekind, const int tid_) {
;     ...
;     LDB(B0, 0, 0); SCHED; LDA(At, 0, 0); STAGE(SA(1, 1), A1, offA, t + 1);
;     WAIT_L(8); BAR; WAIT_L(0); MMA(0, 0, At, B0); BAR; SCHED;
;     LDB(B1, 0, 1); STAGE(SB(0, 0), B0p, offB, t + 2);
;     BAR; WAIT_L(0); MMA(0, 1, At, B1); BAR;
;     LDA(At, 0, 1); STAGE(SA(0, 0), A0, offA, t + 2);
;     BAR; WAIT_L(0); MMA(1, 0, At, B0); BAR; SCHED;
.LBB0_313:
	ds_read_b128 v[180:183], v161
	ds_read_b128 v[184:187], v161 offset:1024
	ds_read_b128 v[188:191], v161 offset:2048
	ds_read_b128 v[192:195], v161 offset:3072
	v_add_u32_e32 v168, s11, v162
	v_add_u32_e32 v164, 0xc000, v145
	v_add_u32_e32 v0, 64, v168
	v_readfirstlane_b32 s45, v164
	v_add_u32_e32 v179, s11, v160
	v_add_u32_e32 v165, 0xe000, v145
	v_lshl_add_u64 v[166:167], v[0:1], 1, s[2:3]
	s_mov_b32 m0, s45
	v_add_u32_e32 v0, 64, v179
	v_readfirstlane_b32 s45, v165
	ds_read_b128 v[196:199], v141
	ds_read_b128 v[200:203], v141 offset:1024
	ds_read_b128 v[204:207], v140
	ds_read_b128 v[208:211], v140 offset:1024
	ds_read_b128 v[212:215], v139
	ds_read_b128 v[216:219], v139 offset:1024
	ds_read_b128 v[220:223], v138
	ds_read_b128 v[224:227], v138 offset:1024
	global_load_lds_dwordx4 v[166:167], off
	v_lshl_add_u64 v[166:167], v[0:1], 1, s[2:3]
	s_mov_b32 m0, s45
	s_nop 0
	global_load_lds_dwordx4 v[166:167], off
	s_waitcnt lgkmcnt(8)
	s_barrier
	s_waitcnt lgkmcnt(0)
	s_setprio 1
	v_mfma_f32_16x16x32_bf16 v[126:129], v[180:183], v[196:199], v[126:129]
	v_mfma_f32_16x16x32_bf16 v[122:125], v[188:191], v[196:199], v[122:125]
	v_mfma_f32_16x16x32_bf16 v[118:121], v[180:183], v[204:207], v[118:121]
	v_mfma_f32_16x16x32_bf16 v[114:117], v[188:191], v[204:207], v[114:117]
	v_mfma_f32_16x16x32_bf16 v[110:113], v[180:183], v[212:215], v[110:113]
	v_mfma_f32_16x16x32_bf16 v[106:109], v[188:191], v[212:215], v[106:109]
	v_mfma_f32_16x16x32_bf16 v[102:105], v[180:183], v[220:223], v[102:105]
	v_mfma_f32_16x16x32_bf16 v[98:101], v[188:191], v[220:223], v[98:101]
	v_mfma_f32_16x16x32_bf16 v[126:129], v[184:187], v[200:203], v[126:129]
	v_mfma_f32_16x16x32_bf16 v[122:125], v[192:195], v[200:203], v[122:125]
	v_mfma_f32_16x16x32_bf16 v[118:121], v[184:187], v[208:211], v[118:121]
	v_mfma_f32_16x16x32_bf16 v[114:117], v[192:195], v[208:211], v[114:117]
	v_mfma_f32_16x16x32_bf16 v[110:113], v[184:187], v[216:219], v[110:113]
	v_mfma_f32_16x16x32_bf16 v[106:109], v[192:195], v[216:219], v[106:109]
	v_mfma_f32_16x16x32_bf16 v[102:105], v[184:187], v[224:227], v[102:105]
	v_mfma_f32_16x16x32_bf16 v[98:101], v[192:195], v[224:227], v[98:101]
	s_setprio 0
	s_barrier
	v_add_u32_e32 v252, s11, v163
	v_add_u32_e32 v0, 0x80, v252
	v_lshlrev_b64 v[166:167], 1, v[0:1]
	v_readfirstlane_b32 s45, v143
	v_add_u32_e32 v169, s11, v134
	v_lshl_add_u64 v[244:245], s[6:7], 0, v[166:167]
	s_mov_b32 m0, s45
	v_add_u32_e32 v0, 0x80, v169
	ds_read_b128 v[228:231], v156
	ds_read_b128 v[232:235], v156 offset:1024
	ds_read_b128 v[236:239], v156 offset:2048
	ds_read_b128 v[240:243], v156 offset:3072
	global_load_lds_dwordx4 v[244:245], off
	v_lshlrev_b64 v[244:245], 1, v[0:1]
	v_readfirstlane_b32 s45, v144
	v_lshl_add_u64 v[246:247], s[6:7], 0, v[244:245]
	s_mov_b32 m0, s45
	s_add_i32 s42, s42, 2
	global_load_lds_dwordx4 v[246:247], off
	s_barrier
	s_waitcnt lgkmcnt(0)
	s_setprio 1
	v_mfma_f32_16x16x32_bf16 v[94:97], v[228:231], v[196:199], v[94:97]
	v_mfma_f32_16x16x32_bf16 v[90:93], v[236:239], v[196:199], v[90:93]
	v_mfma_f32_16x16x32_bf16 v[86:89], v[228:231], v[204:207], v[86:89]
	v_mfma_f32_16x16x32_bf16 v[82:85], v[236:239], v[204:207], v[82:85]
	v_mfma_f32_16x16x32_bf16 v[78:81], v[228:231], v[212:215], v[78:81]
	v_mfma_f32_16x16x32_bf16 v[74:77], v[236:239], v[212:215], v[74:77]
	v_mfma_f32_16x16x32_bf16 v[70:73], v[228:231], v[220:223], v[70:73]
	v_mfma_f32_16x16x32_bf16 v[66:69], v[236:239], v[220:223], v[66:69]
	v_mfma_f32_16x16x32_bf16 v[94:97], v[232:235], v[200:203], v[94:97]
	v_mfma_f32_16x16x32_bf16 v[90:93], v[240:243], v[200:203], v[90:93]
	v_mfma_f32_16x16x32_bf16 v[86:89], v[232:235], v[208:211], v[86:89]
	v_mfma_f32_16x16x32_bf16 v[82:85], v[240:243], v[208:211], v[82:85]
	v_mfma_f32_16x16x32_bf16 v[78:81], v[232:235], v[216:219], v[78:81]
	v_mfma_f32_16x16x32_bf16 v[74:77], v[240:243], v[216:219], v[74:77]
	v_mfma_f32_16x16x32_bf16 v[70:73], v[232:235], v[224:227], v[70:73]
	v_mfma_f32_16x16x32_bf16 v[66:69], v[240:243], v[224:227], v[66:69]
	s_setprio 0
	v_add_u32_e32 v0, 0x80, v168
	v_lshlrev_b64 v[246:247], 1, v[0:1]
	v_readfirstlane_b32 s45, v145
	v_lshl_add_u64 v[248:249], s[4:5], 0, v[246:247]
	s_mov_b32 m0, s45
	v_add_u32_e32 v0, 0x80, v179
	s_barrier
	ds_read_b128 v[196:199], v141 offset:16384
	ds_read_b128 v[200:203], v141 offset:17408
	ds_read_b128 v[204:207], v140 offset:16384
	ds_read_b128 v[208:211], v140 offset:17408
	ds_read_b128 v[212:215], v139 offset:16384
	ds_read_b128 v[216:219], v139 offset:17408
	ds_read_b128 v[220:223], v138 offset:16384
	ds_read_b128 v[224:227], v138 offset:17408
	global_load_lds_dwordx4 v[248:249], off
	v_lshlrev_b64 v[248:249], 1, v[0:1]
	v_readfirstlane_b32 s45, v148
	v_lshl_add_u64 v[250:251], s[4:5], 0, v[248:249]
	s_mov_b32 m0, s45
	s_nop 0
	global_load_lds_dwordx4 v[250:251], off
	s_barrier
	s_waitcnt lgkmcnt(0)
	s_setprio 1
	v_mfma_f32_16x16x32_bf16 v[62:65], v[180:183], v[196:199], v[62:65]
	v_mfma_f32_16x16x32_bf16 v[58:61], v[188:191], v[196:199], v[58:61]
	v_mfma_f32_16x16x32_bf16 v[54:57], v[180:183], v[204:207], v[54:57]
	v_mfma_f32_16x16x32_bf16 v[50:53], v[188:191], v[204:207], v[50:53]
	v_mfma_f32_16x16x32_bf16 v[46:49], v[180:183], v[212:215], v[46:49]
	v_mfma_f32_16x16x32_bf16 v[42:45], v[188:191], v[212:215], v[42:45]
	v_mfma_f32_16x16x32_bf16 v[38:41], v[180:183], v[220:223], v[38:41]
	v_mfma_f32_16x16x32_bf16 v[34:37], v[188:191], v[220:223], v[34:37]
	v_mfma_f32_16x16x32_bf16 v[62:65], v[184:187], v[200:203], v[62:65]
	v_mfma_f32_16x16x32_bf16 v[58:61], v[192:195], v[200:203], v[58:61]
	v_mfma_f32_16x16x32_bf16 v[54:57], v[184:187], v[208:211], v[54:57]
	v_mfma_f32_16x16x32_bf16 v[50:53], v[192:195], v[208:211], v[50:53]
	v_mfma_f32_16x16x32_bf16 v[46:49], v[184:187], v[216:219], v[46:49]
	v_mfma_f32_16x16x32_bf16 v[42:45], v[192:195], v[216:219], v[42:45]
	v_mfma_f32_16x16x32_bf16 v[38:41], v[184:187], v[224:227], v[38:41]
	v_mfma_f32_16x16x32_bf16 v[34:37], v[192:195], v[224:227], v[34:37]
	s_setprio 0
	s_barrier
; #define WAIT_V(n) asm volatile("s_waitcnt vmcnt(%0)" ::"n"(n) : "memory")
; #define WAIT_L(n) asm volatile("s_waitcnt lgkmcnt(%0)" ::"n"(n) : "memory")
; #define STAGE(P, BASE, OFF, kt) do { \
;     __builtin_amdgcn_global_load_lds((const unsigned*)((BASE) + (OFF[0] + (unsigned)(kt) * BK)), (unsigned*)((char*)(P) + wid * 1024), 16, 0, 0); \
;     __builtin_amdgcn_global_load_lds((const unsigned*)((BASE) + (OFF[1] + (unsigned)(kt) * BK)), (unsigned*)((char*)(P) + wid * 1024 + 8192), 16, 0, 0); } while (0)
; #define LDA(dst, b, h) for (int m = 0; m < 4; ++m) for (int k = 0; k < 2; ++k) \
;     dst[m][k] = *reinterpret_cast<const bf16x8*>((char*)SA(b, h) + lds_byte(wr * 64 + m * 16 + fr, k * 32 + fq * 8))
; #define LDB(dst, b, h) for (int n = 0; n < 2; ++n) for (int k = 0; k < 2; ++k) \
;     dst[n][k] = *reinterpret_cast<const bf16x8*>((char*)SB(b, h) + lds_byte(wc * 32 + n * 16 + fr, k * 32 + fq * 8))
; #define MMA(ai, bj, At_, Bt_) do { __builtin_amdgcn_s_setprio(1); \
;     for (int m = 0; m < 4; ++m) for (int n = 0; n < 2; ++n) for (int k = 0; k < 2; ++k) \
;       acc[ai][bj][m][n] = __builtin_amdgcn_mfma_f32_16x16x32_bf16(Bt_[n][k], At_[m][k], acc[ai][bj][m][n], 0, 0, 0); \
;     __builtin_amdgcn_s_setprio(0); } while (0)
; #define BAR __builtin_amdgcn_s_barrier()
; #define SCHED __builtin_amdgcn_sched_barrier(0)
; DEVI void gemm_tile(const Params& p, int layer, const u16* __restrict__ A, unsigned lda, const u16* __restrict__ Bt, unsigned ldb, int K,
;                     int brow, int bcol, int ekind, const int tid_) {
;     ...
;     STAGE(SB(0, 1), B1p, offB, t + 2);
;     WAIT_V(6); BAR; MMA(1, 1, At, B1); BAR;
;     LDB(B0, 1, 0); SCHED; LDA(At, 1, 0); STAGE(SA(0, 1), A1, offA, t + 2);
;     WAIT_L(8); BAR; WAIT_L(0); MMA(0, 0, At, B0); BAR; SCHED;
;     LDB(B1, 1, 1); STAGE(SB(1, 0), B0p, offB, t + 3);
;     BAR; WAIT_L(0); MMA(0, 1, At, B1); BAR;
;     LDA(At, 1, 1); STAGE(SA(1, 0), A0, offA, t + 3);
	v_readfirstlane_b32 s45, v149
	v_lshl_add_u64 v[166:167], s[8:9], 0, v[166:167]
	s_mov_b32 m0, s45
	v_readfirstlane_b32 s45, v150
	global_load_lds_dwordx4 v[166:167], off
	v_lshl_add_u64 v[166:167], s[8:9], 0, v[244:245]
	s_mov_b32 m0, s45
	s_nop 0
	global_load_lds_dwordx4 v[166:167], off
	s_waitcnt vmcnt(6)
	s_barrier
	s_setprio 1
	v_mfma_f32_16x16x32_bf16 v[30:33], v[228:231], v[196:199], v[30:33]
	v_mfma_f32_16x16x32_bf16 v[26:29], v[236:239], v[196:199], v[26:29]
	v_mfma_f32_16x16x32_bf16 v[22:25], v[228:231], v[204:207], v[22:25]
	v_mfma_f32_16x16x32_bf16 v[18:21], v[236:239], v[204:207], v[18:21]
	v_mfma_f32_16x16x32_bf16 v[14:17], v[228:231], v[212:215], v[14:17]
	v_mfma_f32_16x16x32_bf16 v[10:13], v[236:239], v[212:215], v[10:13]
	v_mfma_f32_16x16x32_bf16 v[6:9], v[228:231], v[220:223], v[6:9]
	v_mfma_f32_16x16x32_bf16 v[2:5], v[236:239], v[220:223], v[2:5]
	v_mfma_f32_16x16x32_bf16 v[30:33], v[232:235], v[200:203], v[30:33]
	v_mfma_f32_16x16x32_bf16 v[26:29], v[240:243], v[200:203], v[26:29]
	v_mfma_f32_16x16x32_bf16 v[22:25], v[232:235], v[208:211], v[22:25]
	v_mfma_f32_16x16x32_bf16 v[18:21], v[240:243], v[208:211], v[18:21]
	v_mfma_f32_16x16x32_bf16 v[14:17], v[232:235], v[216:219], v[14:17]
	v_mfma_f32_16x16x32_bf16 v[10:13], v[240:243], v[216:219], v[10:13]
	v_mfma_f32_16x16x32_bf16 v[6:9], v[232:235], v[224:227], v[6:9]
	v_mfma_f32_16x16x32_bf16 v[2:5], v[240:243], v[224:227], v[2:5]
	s_setprio 0
	s_barrier
	ds_read_b128 v[180:183], v147
	ds_read_b128 v[184:187], v147 offset:1024
	ds_read_b128 v[188:191], v147 offset:2048
	ds_read_b128 v[192:195], v147 offset:3072
	v_readfirstlane_b32 s45, v151
	v_lshl_add_u64 v[166:167], s[2:3], 0, v[246:247]
	s_mov_b32 m0, s45
	v_readfirstlane_b32 s45, v152
	ds_read_b128 v[196:199], v141 offset:32768
	ds_read_b128 v[200:203], v141 offset:33792
	ds_read_b128 v[204:207], v140 offset:32768
	ds_read_b128 v[208:211], v140 offset:33792
	ds_read_b128 v[212:215], v139 offset:32768
	ds_read_b128 v[216:219], v139 offset:33792
	ds_read_b128 v[220:223], v138 offset:32768
	ds_read_b128 v[224:227], v138 offset:33792
	global_load_lds_dwordx4 v[166:167], off
	v_lshl_add_u64 v[166:167], s[2:3], 0, v[248:249]
	s_mov_b32 m0, s45
	s_nop 0
	global_load_lds_dwordx4 v[166:167], off
	s_waitcnt lgkmcnt(8)
	s_barrier
	s_waitcnt lgkmcnt(0)
	s_setprio 1
	v_mfma_f32_16x16x32_bf16 v[126:129], v[180:183], v[196:199], v[126:129]
	v_mfma_f32_16x16x32_bf16 v[122:125], v[188:191], v[196:199], v[122:125]
	v_mfma_f32_16x16x32_bf16 v[118:121], v[180:183], v[204:207], v[118:121]
	v_mfma_f32_16x16x32_bf16 v[114:117], v[188:191], v[204:207], v[114:117]
	v_mfma_f32_16x16x32_bf16 v[110:113], v[180:183], v[212:215], v[110:113]
	v_mfma_f32_16x16x32_bf16 v[106:109], v[188:191], v[212:215], v[106:109]
	v_mfma_f32_16x16x32_bf16 v[102:105], v[180:183], v[220:223], v[102:105]
	v_mfma_f32_16x16x32_bf16 v[98:101], v[188:191], v[220:223], v[98:101]
	v_mfma_f32_16x16x32_bf16 v[126:129], v[184:187], v[200:203], v[126:129]
	v_mfma_f32_16x16x32_bf16 v[122:125], v[192:195], v[200:203], v[122:125]
	v_mfma_f32_16x16x32_bf16 v[118:121], v[184:187], v[208:211], v[118:121]
	v_mfma_f32_16x16x32_bf16 v[114:117], v[192:195], v[208:211], v[114:117]
	v_mfma_f32_16x16x32_bf16 v[110:113], v[184:187], v[216:219], v[110:113]
	v_mfma_f32_16x16x32_bf16 v[106:109], v[192:195], v[216:219], v[106:109]
	v_mfma_f32_16x16x32_bf16 v[102:105], v[184:187], v[224:227], v[102:105]
	v_mfma_f32_16x16x32_bf16 v[98:101], v[192:195], v[224:227], v[98:101]
	s_setprio 0
	s_barrier
	v_add_u32_e32 v0, 0xc0, v252
	v_lshlrev_b64 v[166:167], 1, v[0:1]
	v_readfirstlane_b32 s45, v153
	v_lshl_add_u64 v[244:245], s[6:7], 0, v[166:167]
	s_mov_b32 m0, s45
	v_add_u32_e32 v0, 0xc0, v169
	ds_read_b128 v[228:231], v142
	ds_read_b128 v[232:235], v142 offset:1024
	ds_read_b128 v[236:239], v142 offset:2048
	ds_read_b128 v[240:243], v142 offset:3072
	global_load_lds_dwordx4 v[244:245], off
	v_lshlrev_b64 v[244:245], 1, v[0:1]
	v_readfirstlane_b32 s45, v154
	v_lshl_add_u64 v[246:247], s[6:7], 0, v[244:245]
	s_mov_b32 m0, s45
	s_nop 0
	global_load_lds_dwordx4 v[246:247], off
	s_barrier
	s_waitcnt lgkmcnt(0)
	s_setprio 1
	v_mfma_f32_16x16x32_bf16 v[94:97], v[228:231], v[196:199], v[94:97]
	v_mfma_f32_16x16x32_bf16 v[90:93], v[236:239], v[196:199], v[90:93]
	v_mfma_f32_16x16x32_bf16 v[86:89], v[228:231], v[204:207], v[86:89]
	v_mfma_f32_16x16x32_bf16 v[82:85], v[236:239], v[204:207], v[82:85]
	v_mfma_f32_16x16x32_bf16 v[78:81], v[228:231], v[212:215], v[78:81]
	v_mfma_f32_16x16x32_bf16 v[74:77], v[236:239], v[212:215], v[74:77]
	v_mfma_f32_16x16x32_bf16 v[70:73], v[228:231], v[220:223], v[70:73]
	v_mfma_f32_16x16x32_bf16 v[66:69], v[236:239], v[220:223], v[66:69]
	v_mfma_f32_16x16x32_bf16 v[94:97], v[232:235], v[200:203], v[94:97]
	v_mfma_f32_16x16x32_bf16 v[90:93], v[240:243], v[200:203], v[90:93]
	v_mfma_f32_16x16x32_bf16 v[86:89], v[232:235], v[208:211], v[86:89]
	v_mfma_f32_16x16x32_bf16 v[82:85], v[240:243], v[208:211], v[82:85]
	v_mfma_f32_16x16x32_bf16 v[78:81], v[232:235], v[216:219], v[78:81]
	v_mfma_f32_16x16x32_bf16 v[74:77], v[240:243], v[216:219], v[74:77]
	v_mfma_f32_16x16x32_bf16 v[70:73], v[232:235], v[224:227], v[70:73]
	v_mfma_f32_16x16x32_bf16 v[66:69], v[240:243], v[224:227], v[66:69]
	s_setprio 0
	v_add_u32_e32 v0, 0xc0, v168
	v_readfirstlane_b32 s45, v155
	v_lshl_add_u64 v[246:247], v[0:1], 1, s[4:5]
	s_mov_b32 m0, s45
	v_add_u32_e32 v0, 0xc0, v179
	v_readfirstlane_b32 s45, v157
	s_barrier
; #define WAIT_V(n) asm volatile("s_waitcnt vmcnt(%0)" ::"n"(n) : "memory")
; #define WAIT_L(n) asm volatile("s_waitcnt lgkmcnt(%0)" ::"n"(n) : "memory")
; #define STAGE(P, BASE, OFF, kt) do { \
;     __builtin_amdgcn_global_load_lds((const unsigned*)((BASE) + (OFF[0] + (unsigned)(kt) * BK)), (unsigned*)((char*)(P) + wid * 1024), 16, 0, 0); \
;     __builtin_amdgcn_global_load_lds((const unsigned*)((BASE) + (OFF[1] + (unsigned)(kt) * BK)), (unsigned*)((char*)(P) + wid * 1024 + 8192), 16, 0, 0); } while (0)
; #define LDA(dst, b, h) for (int m = 0; m < 4; ++m) for (int k = 0; k < 2; ++k) \
;     dst[m][k] = *reinterpret_cast<const bf16x8*>((char*)SA(b, h) + lds_byte(wr * 64 + m * 16 + fr, k * 32 + fq * 8))
; #define LDB(dst, b, h) for (int n = 0; n < 2; ++n) for (int k = 0; k < 2; ++k) \
;     dst[n][k] = *reinterpret_cast<const bf16x8*>((char*)SB(b, h) + lds_byte(wc * 32 + n * 16 + fr, k * 32 + fq * 8))
; #define MMA(ai, bj, At_, Bt_) do { __builtin_amdgcn_s_setprio(1); \
;     for (int m = 0; m < 4; ++m) for (int n = 0; n < 2; ++n) for (int k = 0; k < 2; ++k) \
;       acc[ai][bj][m][n] = __builtin_amdgcn_mfma_f32_16x16x32_bf16(Bt_[n][k], At_[m][k], acc[ai][bj][m][n], 0, 0, 0); \
;     __builtin_amdgcn_s_setprio(0); } while (0)
; #define BAR __builtin_amdgcn_s_barrier()
; #define SCHED __builtin_amdgcn_sched_barrier(0)
; DEVI void gemm_tile(const Params& p, int layer, const u16* __restrict__ A, unsigned lda, const u16* __restrict__ Bt, unsigned ldb, int K,
;                     int brow, int bcol, int ekind, const int tid_) {
;     ...
;     LDA(At, 1, 1); STAGE(SA(1, 0), A0, offA, t + 3);
;     BAR; WAIT_L(0); MMA(1, 0, At, B0); BAR; SCHED;
;     STAGE(SB(1, 1), B1p, offB, t + 3);
;     WAIT_V(6); BAR; MMA(1, 1, At, B1); BAR;
;   }
;   { LDB(B0, 0, 0); LDA(At, 0, 0); STAGE(SA(1, 1), A1, offA, nt - 1);
;     BAR; WAIT_L(0); MMA(0, 0, At, B0); BAR;
;     LDB(B1, 0, 1); BAR; WAIT_L(0); MMA(0, 1, At, B1); BAR;
	ds_read_b128 v[196:199], v141 offset:49152
	ds_read_b128 v[200:203], v141 offset:50176
	ds_read_b128 v[204:207], v140 offset:49152
	ds_read_b128 v[208:211], v140 offset:50176
	ds_read_b128 v[212:215], v139 offset:49152
	ds_read_b128 v[216:219], v139 offset:50176
	ds_read_b128 v[220:223], v138 offset:49152
	ds_read_b128 v[224:227], v138 offset:50176
	global_load_lds_dwordx4 v[246:247], off
	v_lshl_add_u64 v[246:247], v[0:1], 1, s[4:5]
	s_mov_b32 m0, s45
	s_nop 0
	global_load_lds_dwordx4 v[246:247], off
	s_barrier
	s_waitcnt lgkmcnt(0)
	s_setprio 1
	v_mfma_f32_16x16x32_bf16 v[62:65], v[180:183], v[196:199], v[62:65]
	v_mfma_f32_16x16x32_bf16 v[58:61], v[188:191], v[196:199], v[58:61]
	v_mfma_f32_16x16x32_bf16 v[54:57], v[180:183], v[204:207], v[54:57]
	v_mfma_f32_16x16x32_bf16 v[50:53], v[188:191], v[204:207], v[50:53]
	v_mfma_f32_16x16x32_bf16 v[46:49], v[180:183], v[212:215], v[46:49]
	v_mfma_f32_16x16x32_bf16 v[42:45], v[188:191], v[212:215], v[42:45]
	v_mfma_f32_16x16x32_bf16 v[38:41], v[180:183], v[220:223], v[38:41]
	v_mfma_f32_16x16x32_bf16 v[34:37], v[188:191], v[220:223], v[34:37]
	v_mfma_f32_16x16x32_bf16 v[62:65], v[184:187], v[200:203], v[62:65]
	v_mfma_f32_16x16x32_bf16 v[58:61], v[192:195], v[200:203], v[58:61]
	v_mfma_f32_16x16x32_bf16 v[54:57], v[184:187], v[208:211], v[54:57]
	v_mfma_f32_16x16x32_bf16 v[50:53], v[192:195], v[208:211], v[50:53]
	v_mfma_f32_16x16x32_bf16 v[46:49], v[184:187], v[216:219], v[46:49]
	v_mfma_f32_16x16x32_bf16 v[42:45], v[192:195], v[216:219], v[42:45]
	v_mfma_f32_16x16x32_bf16 v[38:41], v[184:187], v[224:227], v[38:41]
	v_mfma_f32_16x16x32_bf16 v[34:37], v[192:195], v[224:227], v[34:37]
	s_setprio 0
	s_barrier
	v_readfirstlane_b32 s45, v158
	v_lshl_add_u64 v[166:167], s[8:9], 0, v[166:167]
	s_mov_b32 m0, s45
	v_readfirstlane_b32 s45, v159
	global_load_lds_dwordx4 v[166:167], off
	v_lshl_add_u64 v[166:167], s[8:9], 0, v[244:245]
	s_mov_b32 m0, s45
	s_nop 0
	global_load_lds_dwordx4 v[166:167], off
	s_waitcnt vmcnt(6)
	s_barrier
	s_setprio 1
	v_mfma_f32_16x16x32_bf16 v[30:33], v[228:231], v[196:199], v[30:33]
	v_mfma_f32_16x16x32_bf16 v[26:29], v[236:239], v[196:199], v[26:29]
	v_mfma_f32_16x16x32_bf16 v[22:25], v[228:231], v[204:207], v[22:25]
	v_mfma_f32_16x16x32_bf16 v[18:21], v[236:239], v[204:207], v[18:21]
	v_mfma_f32_16x16x32_bf16 v[14:17], v[228:231], v[212:215], v[14:17]
	v_mfma_f32_16x16x32_bf16 v[10:13], v[236:239], v[212:215], v[10:13]
	v_mfma_f32_16x16x32_bf16 v[6:9], v[228:231], v[220:223], v[6:9]
	v_mfma_f32_16x16x32_bf16 v[2:5], v[236:239], v[220:223], v[2:5]
	v_mfma_f32_16x16x32_bf16 v[30:33], v[232:235], v[200:203], v[30:33]
	v_mfma_f32_16x16x32_bf16 v[26:29], v[240:243], v[200:203], v[26:29]
	v_mfma_f32_16x16x32_bf16 v[22:25], v[232:235], v[208:211], v[22:25]
	v_mfma_f32_16x16x32_bf16 v[18:21], v[240:243], v[208:211], v[18:21]
	v_mfma_f32_16x16x32_bf16 v[14:17], v[232:235], v[216:219], v[14:17]
	v_mfma_f32_16x16x32_bf16 v[10:13], v[240:243], v[216:219], v[10:13]
	v_mfma_f32_16x16x32_bf16 v[6:9], v[232:235], v[224:227], v[6:9]
	v_mfma_f32_16x16x32_bf16 v[2:5], v[240:243], v[224:227], v[2:5]
	s_setprio 0
	s_addk_i32 s11, 0x80
	s_cmp_lt_u32 s42, s10
	s_barrier
	s_cbranch_scc1 .LBB0_313
	s_sub_i32 s4, s66, 64
	v_add_u32_e32 v0, s4, v130
	v_readfirstlane_b32 s5, v164
	v_lshl_add_u64 v[144:145], v[0:1], 1, s[2:3]
	s_mov_b32 m0, s5
	v_add_u32_e32 v0, s4, v132
	ds_read_b128 v[148:151], v161
	ds_read_b128 v[152:155], v161 offset:1024
	ds_read_b128 v[180:183], v161 offset:2048
	ds_read_b128 v[158:161], v161 offset:3072
	ds_read_b128 v[184:187], v141
	ds_read_b128 v[188:191], v141 offset:1024
	ds_read_b128 v[192:195], v140
	ds_read_b128 v[196:199], v140 offset:1024
	ds_read_b128 v[200:203], v139
	ds_read_b128 v[204:207], v139 offset:1024
	ds_read_b128 v[208:211], v138
	ds_read_b128 v[212:215], v138 offset:1024
	global_load_lds_dwordx4 v[144:145], off
	v_lshl_add_u64 v[144:145], v[0:1], 1, s[2:3]
	v_readfirstlane_b32 s2, v165
	s_mov_b32 m0, s2
	s_nop 0
	global_load_lds_dwordx4 v[144:145], off
	s_barrier
	s_waitcnt lgkmcnt(0)
	s_setprio 1
	v_mfma_f32_16x16x32_bf16 v[126:129], v[148:151], v[184:187], v[126:129]
	v_mfma_f32_16x16x32_bf16 v[122:125], v[180:183], v[184:187], v[122:125]
	v_mfma_f32_16x16x32_bf16 v[118:121], v[148:151], v[192:195], v[118:121]
	v_mfma_f32_16x16x32_bf16 v[114:117], v[180:183], v[192:195], v[114:117]
	v_mfma_f32_16x16x32_bf16 v[102:105], v[148:151], v[208:211], v[102:105]
	v_mfma_f32_16x16x32_bf16 v[98:101], v[180:183], v[208:211], v[98:101]
	v_mfma_f32_16x16x32_bf16 v[126:129], v[152:155], v[188:191], v[126:129]
	v_mfma_f32_16x16x32_bf16 v[122:125], v[158:161], v[188:191], v[122:125]
	v_mfma_f32_16x16x32_bf16 v[118:121], v[152:155], v[196:199], v[118:121]
	v_mfma_f32_16x16x32_bf16 v[114:117], v[158:161], v[196:199], v[114:117]
	v_mfma_f32_16x16x32_bf16 v[110:113], v[148:151], v[200:203], v[110:113]
	v_mfma_f32_16x16x32_bf16 v[106:109], v[180:183], v[200:203], v[106:109]
	v_mfma_f32_16x16x32_bf16 v[102:105], v[152:155], v[212:215], v[102:105]
	v_mfma_f32_16x16x32_bf16 v[98:101], v[158:161], v[212:215], v[98:101]
	v_mfma_f32_16x16x32_bf16 v[162:165], v[152:155], v[204:207], v[110:113]
	v_mfma_f32_16x16x32_bf16 v[216:219], v[158:161], v[204:207], v[106:109]
	s_setprio 0
	s_barrier
	s_nop 1
	ds_read_b128 v[106:109], v156
	ds_read_b128 v[110:113], v156 offset:1024
	ds_read_b128 v[220:223], v156 offset:2048
	ds_read_b128 v[224:227], v156 offset:3072
	s_barrier
; #define WAIT_V(n) asm volatile("s_waitcnt vmcnt(%0)" ::"n"(n) : "memory")
; #define WAIT_L(n) asm volatile("s_waitcnt lgkmcnt(%0)" ::"n"(n) : "memory")
; #define LDA(dst, b, h) for (int m = 0; m < 4; ++m) for (int k = 0; k < 2; ++k) \
;     dst[m][k] = *reinterpret_cast<const bf16x8*>((char*)SA(b, h) + lds_byte(wr * 64 + m * 16 + fr, k * 32 + fq * 8))
; #define LDB(dst, b, h) for (int n = 0; n < 2; ++n) for (int k = 0; k < 2; ++k) \
;     dst[n][k] = *reinterpret_cast<const bf16x8*>((char*)SB(b, h) + lds_byte(wc * 32 + n * 16 + fr, k * 32 + fq * 8))
; #define MMA(ai, bj, At_, Bt_) do { __builtin_amdgcn_s_setprio(1); \
;     for (int m = 0; m < 4; ++m) for (int n = 0; n < 2; ++n) for (int k = 0; k < 2; ++k) \
;       acc[ai][bj][m][n] = __builtin_amdgcn_mfma_f32_16x16x32_bf16(Bt_[n][k], At_[m][k], acc[ai][bj][m][n], 0, 0, 0); \
;     __builtin_amdgcn_s_setprio(0); } while (0)
; #define BAR __builtin_amdgcn_s_barrier()
; DEVI void gemm_tile(const Params& p, int layer, const u16* __restrict__ A, unsigned lda, const u16* __restrict__ Bt, unsigned ldb, int K,
;                     int brow, int bcol, int ekind, const int tid_) {
;     ...
;     LDB(B1, 0, 1); BAR; WAIT_L(0); MMA(0, 1, At, B1); BAR;
;     LDA(At, 0, 1); WAIT_V(4); BAR; WAIT_L(0); MMA(1, 0, At, B0); MMA(1, 1, At, B1); BAR; }
;   { LDB(B0, 1, 0); LDA(At, 1, 0); WAIT_V(2); BAR; WAIT_L(0); MMA(0, 0, At, B0); BAR;
	s_waitcnt lgkmcnt(0)
	s_setprio 1
	v_mfma_f32_16x16x32_bf16 v[86:89], v[106:109], v[192:195], v[86:89]
	v_mfma_f32_16x16x32_bf16 v[82:85], v[220:223], v[192:195], v[82:85]
	v_mfma_f32_16x16x32_bf16 v[70:73], v[106:109], v[208:211], v[70:73]
	v_mfma_f32_16x16x32_bf16 v[66:69], v[220:223], v[208:211], v[66:69]
	v_mfma_f32_16x16x32_bf16 v[94:97], v[106:109], v[184:187], v[94:97]
	v_mfma_f32_16x16x32_bf16 v[90:93], v[220:223], v[184:187], v[90:93]
	v_mfma_f32_16x16x32_bf16 v[86:89], v[110:113], v[196:199], v[86:89]
	v_mfma_f32_16x16x32_bf16 v[82:85], v[224:227], v[196:199], v[82:85]
	v_mfma_f32_16x16x32_bf16 v[78:81], v[106:109], v[200:203], v[78:81]
	v_mfma_f32_16x16x32_bf16 v[74:77], v[220:223], v[200:203], v[74:77]
	v_mfma_f32_16x16x32_bf16 v[70:73], v[110:113], v[212:215], v[70:73]
	v_mfma_f32_16x16x32_bf16 v[66:69], v[224:227], v[212:215], v[66:69]
	v_mfma_f32_16x16x32_bf16 v[228:231], v[110:113], v[188:191], v[94:97]
	v_mfma_f32_16x16x32_bf16 v[184:187], v[224:227], v[188:191], v[90:93]
	v_mfma_f32_16x16x32_bf16 v[188:191], v[110:113], v[204:207], v[78:81]
	v_mfma_f32_16x16x32_bf16 v[192:195], v[224:227], v[204:207], v[74:77]
	s_setprio 0
	s_barrier
	s_nop 0
	ds_read_b128 v[74:77], v141 offset:16384
	ds_read_b128 v[78:81], v141 offset:17408
	ds_read_b128 v[90:93], v140 offset:16384
	ds_read_b128 v[94:97], v140 offset:17408
	ds_read_b128 v[196:199], v139 offset:16384
	ds_read_b128 v[200:203], v139 offset:17408
	ds_read_b128 v[204:207], v138 offset:16384
	ds_read_b128 v[208:211], v138 offset:17408
	s_waitcnt vmcnt(4)
	s_barrier
	s_waitcnt lgkmcnt(0)
	s_setprio 1
	v_mfma_f32_16x16x32_bf16 v[62:65], v[148:151], v[74:77], v[62:65]
	v_mfma_f32_16x16x32_bf16 v[58:61], v[180:183], v[74:77], v[58:61]
	v_mfma_f32_16x16x32_bf16 v[54:57], v[148:151], v[90:93], v[54:57]
	v_mfma_f32_16x16x32_bf16 v[50:53], v[180:183], v[90:93], v[50:53]
	v_mfma_f32_16x16x32_bf16 v[38:41], v[148:151], v[204:207], v[38:41]
	v_mfma_f32_16x16x32_bf16 v[34:37], v[180:183], v[204:207], v[34:37]
	v_mfma_f32_16x16x32_bf16 v[62:65], v[152:155], v[78:81], v[62:65]
	v_mfma_f32_16x16x32_bf16 v[58:61], v[158:161], v[78:81], v[58:61]
	v_mfma_f32_16x16x32_bf16 v[54:57], v[152:155], v[94:97], v[54:57]
	v_mfma_f32_16x16x32_bf16 v[50:53], v[158:161], v[94:97], v[50:53]
	v_mfma_f32_16x16x32_bf16 v[46:49], v[148:151], v[196:199], v[46:49]
	v_mfma_f32_16x16x32_bf16 v[42:45], v[180:183], v[196:199], v[42:45]
	v_mfma_f32_16x16x32_bf16 v[38:41], v[152:155], v[208:211], v[38:41]
	v_mfma_f32_16x16x32_bf16 v[34:37], v[158:161], v[208:211], v[34:37]
	v_mfma_f32_16x16x32_bf16 v[212:215], v[152:155], v[200:203], v[46:49]
	v_mfma_f32_16x16x32_bf16 v[232:235], v[158:161], v[200:203], v[42:45]
	s_setprio 0
	s_setprio 1
	v_mfma_f32_16x16x32_bf16 v[22:25], v[106:109], v[90:93], v[22:25]
	v_mfma_f32_16x16x32_bf16 v[18:21], v[220:223], v[90:93], v[18:21]
	v_mfma_f32_16x16x32_bf16 v[6:9], v[106:109], v[204:207], v[6:9]
	v_mfma_f32_16x16x32_bf16 v[2:5], v[220:223], v[204:207], v[2:5]
	v_mfma_f32_16x16x32_bf16 v[30:33], v[106:109], v[74:77], v[30:33]
	v_mfma_f32_16x16x32_bf16 v[26:29], v[220:223], v[74:77], v[26:29]
	v_mfma_f32_16x16x32_bf16 v[22:25], v[110:113], v[94:97], v[22:25]
	v_mfma_f32_16x16x32_bf16 v[18:21], v[224:227], v[94:97], v[18:21]
	v_mfma_f32_16x16x32_bf16 v[14:17], v[106:109], v[196:199], v[14:17]
	v_mfma_f32_16x16x32_bf16 v[10:13], v[220:223], v[196:199], v[10:13]
	v_mfma_f32_16x16x32_bf16 v[6:9], v[110:113], v[208:211], v[6:9]
	v_mfma_f32_16x16x32_bf16 v[2:5], v[224:227], v[208:211], v[2:5]
	v_mfma_f32_16x16x32_bf16 v[148:151], v[110:113], v[78:81], v[30:33]
	v_mfma_f32_16x16x32_bf16 v[152:155], v[224:227], v[78:81], v[26:29]
	v_mfma_f32_16x16x32_bf16 v[156:159], v[110:113], v[200:203], v[14:17]
	v_mfma_f32_16x16x32_bf16 v[180:183], v[224:227], v[200:203], v[10:13]
	s_setprio 0
	s_barrier
	s_nop 0
	ds_read_b128 v[10:13], v147
	ds_read_b128 v[14:17], v147 offset:1024
	ds_read_b128 v[196:199], v147 offset:2048
	ds_read_b128 v[200:203], v147 offset:3072
	ds_read_b128 v[26:29], v141 offset:32768
	ds_read_b128 v[30:33], v141 offset:33792
	ds_read_b128 v[42:45], v140 offset:32768
	ds_read_b128 v[46:49], v140 offset:33792
	ds_read_b128 v[204:207], v139 offset:32768
	ds_read_b128 v[208:211], v139 offset:33792
	ds_read_b128 v[220:223], v138 offset:32768
	ds_read_b128 v[224:227], v138 offset:33792
	s_waitcnt vmcnt(2)
	s_barrier
; #define WAIT_V(n) asm volatile("s_waitcnt vmcnt(%0)" ::"n"(n) : "memory")
; #define WAIT_L(n) asm volatile("s_waitcnt lgkmcnt(%0)" ::"n"(n) : "memory")
; #define LDA(dst, b, h) for (int m = 0; m < 4; ++m) for (int k = 0; k < 2; ++k) \
;     dst[m][k] = *reinterpret_cast<const bf16x8*>((char*)SA(b, h) + lds_byte(wr * 64 + m * 16 + fr, k * 32 + fq * 8))
; #define LDB(dst, b, h) for (int n = 0; n < 2; ++n) for (int k = 0; k < 2; ++k) \
;     dst[n][k] = *reinterpret_cast<const bf16x8*>((char*)SB(b, h) + lds_byte(wc * 32 + n * 16 + fr, k * 32 + fq * 8))
; #define MMA(ai, bj, At_, Bt_) do { __builtin_amdgcn_s_setprio(1); \
;     for (int m = 0; m < 4; ++m) for (int n = 0; n < 2; ++n) for (int k = 0; k < 2; ++k) \
;       acc[ai][bj][m][n] = __builtin_amdgcn_mfma_f32_16x16x32_bf16(Bt_[n][k], At_[m][k], acc[ai][bj][m][n], 0, 0, 0); \
;     __builtin_amdgcn_s_setprio(0); } while (0)
; #define BAR __builtin_amdgcn_s_barrier()
; DEVI void gemm_tile(const Params& p, int layer, const u16* __restrict__ A, unsigned lda, const u16* __restrict__ Bt, unsigned ldb, int K,
;                     int brow, int bcol, int ekind, const int tid_) {
;     ...
;   { LDB(B0, 1, 0); LDA(At, 1, 0); WAIT_V(2); BAR; WAIT_L(0); MMA(0, 0, At, B0); BAR;
;     LDB(B1, 1, 1); WAIT_V(0); BAR; WAIT_L(0); MMA(0, 1, At, B1); BAR;
;     LDA(At, 1, 1); BAR; WAIT_L(0); MMA(1, 0, At, B0); MMA(1, 1, At, B1); BAR; }
;   if (wr == 0) BAR;
	s_waitcnt lgkmcnt(0)
	s_setprio 1
	v_mfma_f32_16x16x32_bf16 v[74:77], v[10:13], v[26:29], v[126:129]
	v_mfma_f32_16x16x32_bf16 v[126:129], v[14:17], v[30:33], v[74:77]
	v_mfma_f32_16x16x32_bf16 v[74:77], v[196:199], v[26:29], v[122:125]
	v_mfma_f32_16x16x32_bf16 v[122:125], v[200:203], v[30:33], v[74:77]
	v_mfma_f32_16x16x32_bf16 v[74:77], v[10:13], v[42:45], v[118:121]
	v_mfma_f32_16x16x32_bf16 v[110:113], v[14:17], v[46:49], v[74:77]
	v_mfma_f32_16x16x32_bf16 v[74:77], v[196:199], v[42:45], v[114:117]
	v_mfma_f32_16x16x32_bf16 v[106:109], v[200:203], v[46:49], v[74:77]
	v_mfma_f32_16x16x32_bf16 v[74:77], v[10:13], v[204:207], v[162:165]
	v_mfma_f32_16x16x32_bf16 v[94:97], v[14:17], v[208:211], v[74:77]
	v_mfma_f32_16x16x32_bf16 v[74:77], v[196:199], v[204:207], v[216:219]
	v_mfma_f32_16x16x32_bf16 v[90:93], v[200:203], v[208:211], v[74:77]
	v_mfma_f32_16x16x32_bf16 v[74:77], v[10:13], v[220:223], v[102:105]
	v_mfma_f32_16x16x32_bf16 v[78:81], v[14:17], v[224:227], v[74:77]
	v_mfma_f32_16x16x32_bf16 v[74:77], v[196:199], v[220:223], v[98:101]
	v_mfma_f32_16x16x32_bf16 v[74:77], v[200:203], v[224:227], v[74:77]
	s_setprio 0
	s_barrier
	ds_read_b128 v[160:163], v142
	ds_read_b128 v[164:167], v142 offset:1024
	ds_read_b128 v[216:219], v142 offset:2048
	ds_read_b128 v[142:145], v142 offset:3072
	s_waitcnt vmcnt(0)
	s_barrier
	s_waitcnt lgkmcnt(0)
	s_setprio 1
	v_mfma_f32_16x16x32_bf16 v[98:101], v[160:163], v[26:29], v[228:231]
	v_mfma_f32_16x16x32_bf16 v[26:29], v[216:219], v[26:29], v[184:187]
	v_mfma_f32_16x16x32_bf16 v[114:117], v[142:145], v[30:33], v[26:29]
	v_mfma_f32_16x16x32_bf16 v[26:29], v[160:163], v[42:45], v[86:89]
	v_mfma_f32_16x16x32_bf16 v[102:105], v[164:167], v[46:49], v[26:29]
	v_mfma_f32_16x16x32_bf16 v[26:29], v[216:219], v[42:45], v[82:85]
	v_mfma_f32_16x16x32_bf16 v[118:121], v[164:167], v[30:33], v[98:101]
	v_mfma_f32_16x16x32_bf16 v[98:101], v[142:145], v[46:49], v[26:29]
	v_mfma_f32_16x16x32_bf16 v[26:29], v[160:163], v[204:207], v[188:191]
	v_mfma_f32_16x16x32_bf16 v[86:89], v[164:167], v[208:211], v[26:29]
	v_mfma_f32_16x16x32_bf16 v[26:29], v[216:219], v[204:207], v[192:195]
	v_mfma_f32_16x16x32_bf16 v[82:85], v[142:145], v[208:211], v[26:29]
	v_mfma_f32_16x16x32_bf16 v[26:29], v[160:163], v[220:223], v[70:73]
	v_mfma_f32_16x16x32_bf16 v[70:73], v[164:167], v[224:227], v[26:29]
	v_mfma_f32_16x16x32_bf16 v[26:29], v[216:219], v[220:223], v[66:69]
	v_mfma_f32_16x16x32_bf16 v[66:69], v[142:145], v[224:227], v[26:29]
	s_setprio 0
	s_barrier
	ds_read_b128 v[184:187], v141 offset:49152
	ds_read_b128 v[188:191], v141 offset:50176
	ds_read_b128 v[192:195], v140 offset:49152
	ds_read_b128 v[204:207], v140 offset:50176
	ds_read_b128 v[208:211], v139 offset:49152
	ds_read_b128 v[220:223], v139 offset:50176
	ds_read_b128 v[224:227], v138 offset:49152
	ds_read_b128 v[138:141], v138 offset:50176
	s_barrier
	s_waitcnt lgkmcnt(0)
	s_setprio 1
	v_mfma_f32_16x16x32_bf16 v[26:29], v[10:13], v[184:187], v[62:65]
	v_mfma_f32_16x16x32_bf16 v[62:65], v[14:17], v[188:191], v[26:29]
	v_mfma_f32_16x16x32_bf16 v[26:29], v[196:199], v[184:187], v[58:61]
	v_mfma_f32_16x16x32_bf16 v[58:61], v[200:203], v[188:191], v[26:29]
	v_mfma_f32_16x16x32_bf16 v[26:29], v[10:13], v[192:195], v[54:57]
	v_mfma_f32_16x16x32_bf16 v[46:49], v[14:17], v[204:207], v[26:29]
	v_mfma_f32_16x16x32_bf16 v[26:29], v[196:199], v[192:195], v[50:53]
	v_mfma_f32_16x16x32_bf16 v[42:45], v[200:203], v[204:207], v[26:29]
	v_mfma_f32_16x16x32_bf16 v[26:29], v[10:13], v[208:211], v[212:215]
	v_mfma_f32_16x16x32_bf16 v[10:13], v[10:13], v[224:227], v[38:41]
	v_mfma_f32_16x16x32_bf16 v[30:33], v[14:17], v[220:223], v[26:29]
	v_mfma_f32_16x16x32_bf16 v[26:29], v[196:199], v[208:211], v[232:235]
	v_mfma_f32_16x16x32_bf16 v[14:17], v[14:17], v[138:141], v[10:13]
	v_mfma_f32_16x16x32_bf16 v[10:13], v[196:199], v[224:227], v[34:37]
	v_mfma_f32_16x16x32_bf16 v[26:29], v[200:203], v[220:223], v[26:29]
	v_mfma_f32_16x16x32_bf16 v[10:13], v[200:203], v[138:141], v[10:13]
	s_setprio 0
	s_setprio 1
	v_mfma_f32_16x16x32_bf16 v[34:37], v[160:163], v[184:187], v[148:151]
	v_mfma_f32_16x16x32_bf16 v[54:57], v[164:167], v[188:191], v[34:37]
	v_mfma_f32_16x16x32_bf16 v[34:37], v[216:219], v[184:187], v[152:155]
	v_mfma_f32_16x16x32_bf16 v[18:21], v[216:219], v[192:195], v[18:21]
	v_mfma_f32_16x16x32_bf16 v[50:53], v[142:145], v[188:191], v[34:37]
	v_mfma_f32_16x16x32_bf16 v[22:25], v[160:163], v[192:195], v[22:25]
	v_mfma_f32_16x16x32_bf16 v[34:37], v[142:145], v[204:207], v[18:21]
	v_mfma_f32_16x16x32_bf16 v[18:21], v[160:163], v[208:211], v[156:159]
	v_mfma_f32_16x16x32_bf16 v[38:41], v[164:167], v[204:207], v[22:25]
	v_mfma_f32_16x16x32_bf16 v[22:25], v[164:167], v[220:223], v[18:21]
	v_mfma_f32_16x16x32_bf16 v[18:21], v[216:219], v[208:211], v[180:183]
	v_mfma_f32_16x16x32_bf16 v[6:9], v[160:163], v[224:227], v[6:9]
	v_mfma_f32_16x16x32_bf16 v[2:5], v[216:219], v[224:227], v[2:5]
	v_mfma_f32_16x16x32_bf16 v[18:21], v[142:145], v[220:223], v[18:21]
	v_mfma_f32_16x16x32_bf16 v[6:9], v[164:167], v[138:141], v[6:9]
	v_mfma_f32_16x16x32_bf16 v[2:5], v[142:145], v[138:141], v[2:5]
	s_setprio 0
	s_movk_i32 s2, 0x100
	v_cmp_gt_u32_e32 vcc, s2, v136
	s_barrier
	s_and_saveexec_b64 s[2:3], vcc
	s_cbranch_execz .LBB0_316
	s_barrier
